# grid barrier: follower workgroups issue their L1 invalidate (buffer_inv sc1) right after arriving, overlapped with the poll, instead of after the release
# speedup vs baseline: 1.0059x; 1.0059x over previous
.LBB0_651:
	s_or_b64 exec, exec, s[6:7]
	v_cvt_f32_u32_e32 v4, v2
	s_waitcnt vmcnt(0)
	v_readfirstlane_b32 s6, v3
	v_sub_u32_e32 v3, 0, v2
	v_rcp_iflag_f32_e32 v4, v4
	v_add_u32_e32 v5, s6, v1
	v_mul_f32_e32 v4, 0x4f7ffffe, v4
	v_cvt_u32_f32_e32 v4, v4
	v_mul_lo_u32 v1, v3, v4
	v_mul_hi_u32 v1, v4, v1
	v_add_u32_e32 v1, v4, v1
	v_mul_hi_u32 v1, v5, v1
	v_mul_lo_u32 v3, v1, v2
	v_sub_u32_e32 v3, v5, v3
	v_add_u32_e32 v4, 1, v1
	v_cmp_ge_u32_e32 vcc, v3, v2
	s_nop 1
	v_cndmask_b32_e32 v1, v1, v4, vcc
	v_sub_u32_e32 v4, v3, v2
	v_cndmask_b32_e32 v3, v3, v4, vcc
	v_add_u32_e32 v4, 1, v1
	v_cmp_ge_u32_e32 vcc, v3, v2
	v_add_u32_e32 v3, 1, v5
	s_nop 0
	v_cndmask_b32_e32 v1, v1, v4, vcc
	v_mul_lo_u32 v4, v2, v1
	v_add_u32_e32 v2, v4, v2
	v_cmp_ne_u32_e32 vcc, v3, v2
	s_and_saveexec_b64 s[6:7], vcc
	s_xor_b64 s[6:7], exec, s[6:7]
	s_cbranch_execz .LBB0_665
	v_readlane_b32 s8, v245, 9
	v_readlane_b32 s9, v245, 10
	s_waitcnt lgkmcnt(0)
	buffer_inv sc1
	s_nop 3
	global_load_dword v0, v137, s[8:9] sc1
	s_waitcnt vmcnt(0)
	v_cmp_eq_u32_e32 vcc, v0, v1
	s_and_saveexec_b64 s[8:9], vcc
	s_cbranch_execz .LBB0_664
	s_mov_b32 s20, 1
	s_mov_b64 s[10:11], 0
	s_branch .LBB0_655

.LBB0_664:
	s_or_b64 exec, exec, s[8:9]
	s_waitcnt vmcnt(0)
.LBB0_665:
	s_andn2_saveexec_b64 s[6:7], s[6:7]
	s_cbranch_execz .LBB0_685
	s_mov_b64 s[6:7], exec
	buffer_wbl2 sc1
	s_waitcnt lgkmcnt(0)
	s_waitcnt vmcnt(0)
	v_mbcnt_lo_u32_b32 v1, s6, 0
	v_mbcnt_hi_u32_b32 v1, s7, v1
	v_cmp_eq_u32_e32 vcc, 0, v1
	s_and_saveexec_b64 s[8:9], vcc
	s_cbranch_execz .LBB0_668
	s_bcnt1_i32_b64 s6, s[6:7]
	v_mov_b32_e32 v2, s6
	v_readlane_b32 s6, v245, 11
	v_readlane_b32 s7, v245, 12
	s_nop 4
	global_atomic_add v2, v137, v2, s[6:7] sc0
